# speedup vs baseline: 1.0055x; 1.0055x over previous
; __device__ __forceinline__ unsigned pk2(float a, float b) { f2_t x; x[0] = a; x[1] = b; return __builtin_bit_cast(unsigned, __builtin_convertvector(x, bf2_t)); }
; __device__ __forceinline__ void norm_phase(const float* x0, const float* x1, const float* g, u16* dst, int tok0, int ntok) {
;   int tid_ = threadIdx.x; asm volatile("" : "+v"(tid_));
;   int wv = tid_ >> 6, lane = tid_ & 63;
;   float4 gg[4];
;   _Pragma("unroll") for (int i = 0; i < 4; ++i) gg[i] = *reinterpret_cast<const float4*>(g + i * 256 + lane * 4);
;   for (int t4 = (blockIdx.x * 8 + wv) * 4; t4 < ntok; t4 += gridDim.x * 32) {
;     float4 v[4][4];
;     _Pragma("unroll") for (int u = 0; u < 4; ++u) {
;       const float* xr = xrow(x0, x1, tok0 + t4 + u);
;       _Pragma("unroll") for (int i = 0; i < 4; ++i) v[u][i] = *reinterpret_cast<const float4*>(xr + i * 256 + lane * 4);
;     }
;     _Pragma("unroll") for (int u = 0; u < 4; ++u) {
;       float ss = 0.f;
;       _Pragma("unroll") for (int i = 0; i < 4; ++i) ss += v[u][i].x * v[u][i].x + v[u][i].y * v[u][i].y + v[u][i].z * v[u][i].z + v[u][i].w * v[u][i].w;
;       ss = wave_sum(ss, lane);
;       float rs = rsqrtf(ss * (1.f / CM) + 1e-6f);
;       _Pragma("unroll") for (int i = 0; i < 4; ++i) {
;         uint2 o; o.x = pk2(v[u][i].x * rs * gg[i].x, v[u][i].y * rs * gg[i].y); o.y = pk2(v[u][i].z * rs * gg[i].z, v[u][i].w * rs * gg[i].w);
;         *reinterpret_cast<uint2*>(dst + (size_t)(t4 + u) * CM + i * 256 + lane * 4) = o;
;       }
;     }
;   }
; }
.LBB0_2918:
	s_or_b64 exec, exec, s[0:1]
	s_waitcnt vmcnt(3)
	v_mov_b32_e32 v0, v131
	s_barrier
	v_readlane_b32 s0, v246, 5
	v_ashrrev_i32_e32 v1, 4, v0
	v_and_b32_e32 v16, -4, v1
	v_add_u32_e32 v1, s0, v16
	s_mov_b32 s0, 0x18000
	v_cmp_gt_i32_e32 vcc, s0, v1
	s_and_saveexec_b64 s[4:5], vcc
	v_readlane_b32 s16, v246, 22
	s_mov_b32 s3, 0x10000
	s_mov_b32 s8, 0x800000
	s_mov_b32 s9, 0xffff
	s_mov_b32 s10, 0xfffe
	s_mov_b32 s11, 0xfffd
	s_mov_b32 s12, 0x3a800000
	s_mov_b32 s14, 0x358637bd
	v_readlane_b32 s17, v246, 23
	s_cbranch_execz .LBB0_2921
	v_readlane_b32 s0, v246, 28
	v_readlane_b32 s6, v246, 32
	v_lshlrev_b32_e32 v17, 2, v0
	v_readlane_b32 s1, v246, 29
	v_readlane_b32 s7, v246, 33
	s_add_u32 s0, s6, s0
	v_and_b32_e32 v18, 0xfc, v17
	s_addc_u32 s1, s7, s1
	s_waitcnt vmcnt(0)
	v_lshlrev_b32_e32 v12, 2, v18
	global_load_dwordx4 v[0:3], v12, s[0:1]
	global_load_dwordx4 v[4:7], v12, s[0:1] offset:1024
	global_load_dwordx4 v[8:11], v12, s[0:1] offset:2048
	s_nop 0
	global_load_dwordx4 v[12:15], v12, s[0:1] offset:3072
	s_movk_i32 s0, 0x80
	v_bitop3_b32 v65, v17, s0, v185 bitop3:0x6c
	v_lshlrev_b32_e32 v128, 1, v18
	v_readlane_b32 s0, v246, 6
	v_bitop3_b32 v64, v17, 64, v185 bitop3:0x6c
	v_lshl_add_u64 v[48:49], s[54:55], 0, v[128:129]
	v_add_u32_e32 v50, s0, v16
	v_add_u32_e32 v50, 0x16000, v50
	s_mov_b64 s[6:7], 0
	v_lshlrev_b32_e32 v128, 2, v18
.LBB0_2920:
	v_add_u32_e32 v16, -3, v50
	v_cmp_gt_i32_e32 vcc, s3, v16
	v_add_u32_e32 v18, 0xfffefffd, v50
	v_ashrrev_i32_e32 v17, 31, v16
	v_cndmask_b32_e32 v19, 0, v17, vcc
	v_cndmask_b32_e32 v18, v18, v16, vcc
	v_mov_b32_e32 v26, s17
	v_mov_b32_e32 v27, s87
	v_mov_b32_e32 v30, s16
	v_mov_b32_e32 v31, s86
	v_cndmask_b32_e32 v21, v26, v27, vcc
	v_cndmask_b32_e32 v20, v30, v31, vcc
	v_lshlrev_b64 v[18:19], 12, v[18:19]
	v_lshl_add_u64 v[18:19], v[20:21], 0, v[18:19]
	v_add_u32_e32 v22, -2, v50
	v_lshl_add_u64 v[20:21], v[18:19], 0, v[128:129]
	v_cmp_gt_i32_e32 vcc, s9, v16
	v_add_u32_e32 v18, 0xfffefffe, v50
	v_ashrrev_i32_e32 v23, 31, v22
	v_cndmask_b32_e32 v19, 0, v23, vcc
	v_cndmask_b32_e32 v18, v18, v22, vcc
	v_cndmask_b32_e32 v25, v26, v27, vcc
	v_cndmask_b32_e32 v24, v30, v31, vcc
	v_lshlrev_b64 v[18:19], 12, v[18:19]
	v_lshl_add_u64 v[18:19], v[24:25], 0, v[18:19]
	v_add_u32_e32 v54, -1, v50
	v_lshl_add_u64 v[28:29], v[18:19], 0, v[128:129]
	v_cmp_gt_i32_e32 vcc, s10, v16
	v_add_u32_e32 v18, 0xfffeffff, v50
	v_ashrrev_i32_e32 v55, 31, v54
	v_cndmask_b32_e32 v19, 0, v55, vcc
	v_cndmask_b32_e32 v18, v18, v54, vcc
	v_cndmask_b32_e32 v25, v26, v27, vcc
	v_cndmask_b32_e32 v24, v30, v31, vcc
	v_lshlrev_b64 v[18:19], 12, v[18:19]
	v_lshl_add_u64 v[18:19], v[24:25], 0, v[18:19]
	v_lshl_add_u64 v[52:53], v[18:19], 0, v[128:129]
	v_cmp_gt_i32_e32 vcc, s11, v16
	v_add_u32_e32 v18, 0xffff0000, v50
	v_ashrrev_i32_e32 v51, 31, v50
	v_cndmask_b32_e32 v19, 0, v51, vcc
	v_cndmask_b32_e32 v18, v18, v50, vcc
	v_cndmask_b32_e32 v25, v26, v27, vcc
	v_cndmask_b32_e32 v24, v30, v31, vcc
	v_lshlrev_b64 v[18:19], 12, v[18:19]
	v_lshl_add_u64 v[18:19], v[24:25], 0, v[18:19]
	v_lshlrev_b64 v[16:17], 11, v[16:17]
	v_lshl_add_u64 v[58:59], v[18:19], 0, v[128:129]
	v_lshl_add_u64 v[56:57], v[48:49], 0, v[16:17]
	global_load_dwordx4 v[32:35], v[20:21], off
	global_load_dwordx4 v[16:19], v[20:21], off offset:1024
	s_waitcnt vmcnt(1)
	v_mov_b32_e32 v36, v33
	s_waitcnt vmcnt(0)
	v_mov_b32_e32 v37, v17
	v_mov_b32_e32 v30, v32
	v_mov_b32_e32 v31, v16
	v_pk_mul_f32 v[36:37], v[36:37], v[36:37]
	v_mov_b32_e32 v24, v34
	v_mov_b32_e32 v25, v18
	v_pk_fma_f32 v[30:31], v[30:31], v[30:31], v[36:37]
	v_mov_b32_e32 v26, v35
	v_mov_b32_e32 v27, v19
	v_pk_fma_f32 v[24:25], v[24:25], v[24:25], v[30:31]
	s_nop 0
	v_pk_fma_f32 v[62:63], v[26:27], v[26:27], v[24:25]
	global_load_dwordx4 v[40:43], v[20:21], off offset:2048
	global_load_dwordx4 v[24:27], v[20:21], off offset:3072
	s_waitcnt vmcnt(1)
	v_mov_b32_e32 v38, v41
	s_waitcnt vmcnt(0)
	v_mov_b32_e32 v39, v25
	v_mov_b32_e32 v36, v40
	v_mov_b32_e32 v37, v24
	v_pk_mul_f32 v[38:39], v[38:39], v[38:39]
	v_mov_b32_e32 v20, v42
	v_mov_b32_e32 v21, v26
	v_pk_fma_f32 v[36:37], v[36:37], v[36:37], v[38:39]
	v_mov_b32_e32 v30, v43
	v_mov_b32_e32 v31, v27
	v_pk_fma_f32 v[20:21], v[20:21], v[20:21], v[36:37]
	s_nop 0
	v_pk_fma_f32 v[66:67], v[30:31], v[30:31], v[20:21]
	v_lshlrev_b64 v[20:21], 11, v[22:23]
	v_lshl_add_u64 v[60:61], v[48:49], 0, v[20:21]
	global_load_dwordx4 v[36:39], v[28:29], off
	global_load_dwordx4 v[20:23], v[28:29], off offset:1024
	s_waitcnt vmcnt(1)
	v_mov_b32_e32 v68, v37
	s_waitcnt vmcnt(0)
	v_mov_b32_e32 v69, v21
	v_mov_b32_e32 v46, v36
	v_mov_b32_e32 v47, v20
	v_pk_mul_f32 v[68:69], v[68:69], v[68:69]
	v_mov_b32_e32 v30, v38
	v_mov_b32_e32 v31, v22
	v_pk_fma_f32 v[46:47], v[46:47], v[46:47], v[68:69]
	v_mov_b32_e32 v44, v39
	v_mov_b32_e32 v45, v23
	v_pk_fma_f32 v[30:31], v[30:31], v[30:31], v[46:47]
	s_nop 0
	v_pk_fma_f32 v[68:69], v[44:45], v[44:45], v[30:31]
	global_load_dwordx4 v[44:47], v[28:29], off offset:2048
	s_nop 0
	global_load_dwordx4 v[28:31], v[28:29], off offset:3072
	s_waitcnt vmcnt(1)
	v_mov_b32_e32 v76, v45
	s_waitcnt vmcnt(0)
; __device__ __forceinline__ unsigned pk2(float a, float b) { f2_t x; x[0] = a; x[1] = b; return __builtin_bit_cast(unsigned, __builtin_convertvector(x, bf2_t)); }
; __device__ __forceinline__ void norm_phase(const float* x0, const float* x1, const float* g, u16* dst, int tok0, int ntok) {
;     ...
;       const float* xr = xrow(x0, x1, tok0 + t4 + u);
;       _Pragma("unroll") for (int i = 0; i < 4; ++i) v[u][i] = *reinterpret_cast<const float4*>(xr + i * 256 + lane * 4);
;     }
;     _Pragma("unroll") for (int u = 0; u < 4; ++u) {
;       float ss = 0.f;
;       _Pragma("unroll") for (int i = 0; i < 4; ++i) ss += v[u][i].x * v[u][i].x + v[u][i].y * v[u][i].y + v[u][i].z * v[u][i].z + v[u][i].w * v[u][i].w;
;       ss = wave_sum(ss, lane);
;       float rs = rsqrtf(ss * (1.f / CM) + 1e-6f);
;       _Pragma("unroll") for (int i = 0; i < 4; ++i) {
;         uint2 o; o.x = pk2(v[u][i].x * rs * gg[i].x, v[u][i].y * rs * gg[i].y); o.y = pk2(v[u][i].z * rs * gg[i].z, v[u][i].w * rs * gg[i].w);
;         *reinterpret_cast<uint2*>(dst + (size_t)(t4 + u) * CM + i * 256 + lane * 4) = o;
;       }
	v_mov_b32_e32 v77, v29
	v_mov_b32_e32 v74, v44
	v_mov_b32_e32 v75, v28
	v_pk_mul_f32 v[76:77], v[76:77], v[76:77]
	v_mov_b32_e32 v70, v46
	v_mov_b32_e32 v71, v30
	v_pk_fma_f32 v[74:75], v[74:75], v[74:75], v[76:77]
	v_mov_b32_e32 v72, v47
	v_mov_b32_e32 v73, v31
	v_pk_fma_f32 v[70:71], v[70:71], v[70:71], v[74:75]
	s_nop 0
	v_pk_fma_f32 v[70:71], v[72:73], v[72:73], v[70:71]
	v_mov_b32_e32 v72, v68
	v_mov_b32_e32 v73, v62
	v_mov_b32_e32 v62, v69
	v_pk_add_f32 v[62:63], v[72:73], v[62:63]
	v_mov_b32_e32 v68, v70
	v_mov_b32_e32 v69, v66
	v_pk_add_f32 v[62:63], v[62:63], v[68:69]
	v_mov_b32_e32 v66, v71
	v_pk_add_f32 v[62:63], v[62:63], v[66:67]
	s_nop 1
	v_mov_b32_dpp v67, v63 quad_perm:[1,0,3,2] row_mask:0xf bank_mask:0xf bound_ctrl:1
	v_mov_b32_dpp v66, v62 quad_perm:[1,0,3,2] row_mask:0xf bank_mask:0xf bound_ctrl:1
	v_pk_add_f32 v[62:63], v[62:63], v[66:67]
	s_nop 1
	v_mov_b32_dpp v67, v63 quad_perm:[2,3,0,1] row_mask:0xf bank_mask:0xf bound_ctrl:1
	v_mov_b32_dpp v66, v62 quad_perm:[2,3,0,1] row_mask:0xf bank_mask:0xf bound_ctrl:1
	v_pk_add_f32 v[62:63], v[62:63], v[66:67]
	s_nop 1
	v_mov_b32_dpp v67, v63 row_half_mirror row_mask:0xf bank_mask:0xf bound_ctrl:1
	v_mov_b32_dpp v66, v62 row_half_mirror row_mask:0xf bank_mask:0xf bound_ctrl:1
	v_pk_add_f32 v[62:63], v[62:63], v[66:67]
	s_nop 1
	v_mov_b32_dpp v67, v63 row_ror:8 row_mask:0xf bank_mask:0xf bound_ctrl:1
	v_mov_b32_dpp v66, v62 row_ror:8 row_mask:0xf bank_mask:0xf bound_ctrl:1
	v_pk_add_f32 v[62:63], v[62:63], v[66:67]
	ds_bpermute_b32 v67, v64, v63
	ds_bpermute_b32 v66, v64, v62
	s_waitcnt lgkmcnt(0)
	v_pk_add_f32 v[62:63], v[62:63], v[66:67]
	ds_bpermute_b32 v67, v65, v63
	ds_bpermute_b32 v66, v65, v62
	s_waitcnt lgkmcnt(0)
	v_pk_add_f32 v[62:63], v[62:63], v[66:67]
	v_mov_b64_e32 v[66:67], s[14:15]
	v_pk_fma_f32 v[62:63], v[62:63], s[12:13], v[66:67] op_sel_hi:[1,0,0]
	s_nop 0
	v_mul_f32_e32 v68, 0x4b800000, v63
	v_cmp_gt_f32_e64 s[0:1], s8, v63
	v_cmp_gt_f32_e32 vcc, s8, v62
	s_nop 0
	v_cndmask_b32_e64 v63, v63, v68, s[0:1]
	v_rsq_f32_e32 v63, v63
	s_nop 0
	v_mul_f32_e32 v68, 0x45800000, v63
	v_cndmask_b32_e64 v68, v63, v68, s[0:1]
	v_pk_mul_f32 v[16:17], v[16:17], v[68:69] op_sel_hi:[1,0]
	v_pk_mul_f32 v[32:33], v[32:33], v[68:69] op_sel_hi:[1,0]
	v_pk_mul_f32 v[16:17], v[4:5], v[16:17]
	v_pk_mul_f32 v[32:33], v[0:1], v[32:33]
	v_cvt_pk_bf16_f32 v72, v16, v17
	v_pk_mul_f32 v[16:17], v[18:19], v[68:69] op_sel_hi:[1,0]
	v_cvt_pk_bf16_f32 v70, v32, v33
	v_pk_mul_f32 v[16:17], v[6:7], v[16:17]
	v_pk_mul_f32 v[32:33], v[34:35], v[68:69] op_sel_hi:[1,0]
	v_cvt_pk_bf16_f32 v73, v16, v17
	v_pk_mul_f32 v[16:17], v[40:41], v[68:69] op_sel_hi:[1,0]
	v_pk_mul_f32 v[32:33], v[2:3], v[32:33]
	v_pk_mul_f32 v[16:17], v[8:9], v[16:17]
	v_cvt_pk_bf16_f32 v71, v32, v33
	v_cvt_pk_bf16_f32 v74, v16, v17
	v_pk_mul_f32 v[16:17], v[42:43], v[68:69] op_sel_hi:[1,0]
	s_nop 0
	v_pk_mul_f32 v[16:17], v[10:11], v[16:17]
	s_nop 0
	v_cvt_pk_bf16_f32 v75, v16, v17
	v_pk_mul_f32 v[16:17], v[24:25], v[68:69] op_sel_hi:[1,0]
	s_nop 0
	v_pk_mul_f32 v[16:17], v[12:13], v[16:17]
	s_nop 0
	v_cvt_pk_bf16_f32 v76, v16, v17
	v_pk_mul_f32 v[16:17], v[26:27], v[68:69] op_sel_hi:[1,0]
	s_nop 0
	v_pk_mul_f32 v[16:17], v[14:15], v[16:17]
	s_nop 0
	v_cvt_pk_bf16_f32 v77, v16, v17
	v_mul_f32_e32 v16, 0x4b800000, v62
	v_cndmask_b32_e32 v16, v62, v16, vcc
	v_rsq_f32_e32 v16, v16
	s_nop 0
	v_mul_f32_e32 v17, 0x45800000, v16
	v_cndmask_b32_e32 v16, v16, v17, vcc
	v_pk_mul_f32 v[18:19], v[36:37], v[16:17] op_sel_hi:[1,0]
	s_nop 0
	v_pk_mul_f32 v[18:19], v[0:1], v[18:19]
	s_nop 0
	v_cvt_pk_bf16_f32 v62, v18, v19
	v_pk_mul_f32 v[18:19], v[38:39], v[16:17] op_sel_hi:[1,0]
	s_nop 0
	v_pk_mul_f32 v[18:19], v[2:3], v[18:19]
	s_nop 0
	v_cvt_pk_bf16_f32 v63, v18, v19
	v_pk_mul_f32 v[18:19], v[20:21], v[16:17] op_sel_hi:[1,0]
	s_nop 0
	v_pk_mul_f32 v[18:19], v[4:5], v[18:19]
	s_nop 0
	v_cvt_pk_bf16_f32 v68, v18, v19
	v_pk_mul_f32 v[18:19], v[22:23], v[16:17] op_sel_hi:[1,0]
	s_nop 0
	v_pk_mul_f32 v[18:19], v[6:7], v[18:19]
	s_nop 0
	v_cvt_pk_bf16_f32 v69, v18, v19
	v_pk_mul_f32 v[18:19], v[44:45], v[16:17] op_sel_hi:[1,0]
	s_nop 0
	v_pk_mul_f32 v[18:19], v[8:9], v[18:19]
	s_nop 0
	v_cvt_pk_bf16_f32 v78, v18, v19
	v_pk_mul_f32 v[18:19], v[46:47], v[16:17] op_sel_hi:[1,0]
	s_nop 0
	v_pk_mul_f32 v[18:19], v[10:11], v[18:19]
	s_nop 0
	v_cvt_pk_bf16_f32 v79, v18, v19
	v_pk_mul_f32 v[18:19], v[28:29], v[16:17] op_sel_hi:[1,0]
	v_pk_mul_f32 v[16:17], v[30:31], v[16:17] op_sel_hi:[1,0]
	v_pk_mul_f32 v[18:19], v[12:13], v[18:19]
	v_pk_mul_f32 v[16:17], v[14:15], v[16:17]
	v_cvt_pk_bf16_f32 v80, v18, v19
	v_cvt_pk_bf16_f32 v81, v16, v17
	v_lshlrev_b64 v[16:17], 11, v[54:55]
	v_lshl_add_u64 v[54:55], v[48:49], 0, v[16:17]
	global_load_dwordx4 v[16:19], v[52:53], off
	global_load_dwordx4 v[20:23], v[52:53], off offset:1024
	s_waitcnt vmcnt(1)
	v_mov_b32_e32 v30, v17
	s_waitcnt vmcnt(0)
	v_mov_b32_e32 v31, v21
	v_mov_b32_e32 v28, v16
	v_mov_b32_e32 v29, v20
	v_pk_mul_f32 v[30:31], v[30:31], v[30:31]
	v_mov_b32_e32 v24, v18
	v_mov_b32_e32 v25, v22
	v_pk_fma_f32 v[28:29], v[28:29], v[28:29], v[30:31]
	v_mov_b32_e32 v26, v19
	v_mov_b32_e32 v27, v23
	v_pk_fma_f32 v[24:25], v[24:25], v[24:25], v[28:29]
	s_nop 0
	v_pk_fma_f32 v[82:83], v[26:27], v[26:27], v[24:25]
	global_load_dwordx4 v[24:27], v[52:53], off offset:2048
	global_load_dwordx4 v[28:31], v[52:53], off offset:3072
	s_waitcnt vmcnt(1)
	v_mov_b32_e32 v38, v25
	s_waitcnt vmcnt(0)
; __device__ __forceinline__ unsigned pk2(float a, float b) { f2_t x; x[0] = a; x[1] = b; return __builtin_bit_cast(unsigned, __builtin_convertvector(x, bf2_t)); }
; __device__ __forceinline__ void norm_phase(const float* x0, const float* x1, const float* g, u16* dst, int tok0, int ntok) {
;     ...
;       _Pragma("unroll") for (int i = 0; i < 4; ++i) v[u][i] = *reinterpret_cast<const float4*>(xr + i * 256 + lane * 4);
;     }
;     _Pragma("unroll") for (int u = 0; u < 4; ++u) {
;       float ss = 0.f;
;       _Pragma("unroll") for (int i = 0; i < 4; ++i) ss += v[u][i].x * v[u][i].x + v[u][i].y * v[u][i].y + v[u][i].z * v[u][i].z + v[u][i].w * v[u][i].w;
;       ss = wave_sum(ss, lane);
;       float rs = rsqrtf(ss * (1.f / CM) + 1e-6f);
;       _Pragma("unroll") for (int i = 0; i < 4; ++i) {
;         uint2 o; o.x = pk2(v[u][i].x * rs * gg[i].x, v[u][i].y * rs * gg[i].y); o.y = pk2(v[u][i].z * rs * gg[i].z, v[u][i].w * rs * gg[i].w);
;         *reinterpret_cast<uint2*>(dst + (size_t)(t4 + u) * CM + i * 256 + lane * 4) = o;
;       }
;     }
;   }
	v_mov_b32_e32 v39, v29
	v_mov_b32_e32 v36, v24
	v_mov_b32_e32 v37, v28
	v_pk_mul_f32 v[38:39], v[38:39], v[38:39]
	v_mov_b32_e32 v32, v26
	v_mov_b32_e32 v33, v30
	v_pk_fma_f32 v[36:37], v[36:37], v[36:37], v[38:39]
	v_mov_b32_e32 v34, v27
	v_mov_b32_e32 v35, v31
	v_pk_fma_f32 v[32:33], v[32:33], v[32:33], v[36:37]
	s_nop 0
	v_pk_fma_f32 v[52:53], v[34:35], v[34:35], v[32:33]
	v_lshlrev_b64 v[32:33], 11, v[50:51]
	v_lshl_add_u64 v[84:85], v[48:49], 0, v[32:33]
	global_load_dwordx4 v[32:35], v[58:59], off
	global_load_dwordx4 v[36:39], v[58:59], off offset:1024
	v_subrev_u32_e32 v50, s13, v50
	s_waitcnt vmcnt(1)
	v_mov_b32_e32 v46, v33
	s_waitcnt vmcnt(0)
	v_mov_b32_e32 v47, v37
	v_mov_b32_e32 v44, v32
	v_mov_b32_e32 v45, v36
	v_pk_mul_f32 v[46:47], v[46:47], v[46:47]
	v_mov_b32_e32 v40, v34
	v_mov_b32_e32 v41, v38
	v_pk_fma_f32 v[44:45], v[44:45], v[44:45], v[46:47]
	v_mov_b32_e32 v42, v35
	v_mov_b32_e32 v43, v39
	v_pk_fma_f32 v[40:41], v[40:41], v[40:41], v[44:45]
	s_nop 0
	v_pk_fma_f32 v[86:87], v[42:43], v[42:43], v[40:41]
	global_load_dwordx4 v[40:43], v[58:59], off offset:2048
	global_load_dwordx4 v[44:47], v[58:59], off offset:3072
	s_nop 0
	global_store_dwordx2 v[56:57], v[70:71], off
	global_store_dwordx2 v[56:57], v[72:73], off offset:512
	global_store_dwordx2 v[56:57], v[74:75], off offset:1024
	global_store_dwordx2 v[56:57], v[76:77], off offset:1536
	global_store_dwordx2 v[60:61], v[62:63], off
	global_store_dwordx2 v[60:61], v[68:69], off offset:512
	global_store_dwordx2 v[60:61], v[78:79], off offset:1024
	global_store_dwordx2 v[60:61], v[80:81], off offset:1536
	v_mov_b32_e32 v56, v86
	v_mov_b32_e32 v57, v82
	v_mov_b32_e32 v82, v87
	v_pk_add_f32 v[56:57], v[56:57], v[82:83]
	v_mov_b32_e32 v61, v52
	s_waitcnt vmcnt(9)
	v_mov_b32_e32 v92, v41
	s_waitcnt vmcnt(8)
	v_mov_b32_e32 v93, v45
	v_mov_b32_e32 v90, v40
	v_mov_b32_e32 v91, v44
	v_pk_mul_f32 v[92:93], v[92:93], v[92:93]
	v_mov_b32_e32 v58, v42
	v_mov_b32_e32 v59, v46
	v_pk_fma_f32 v[90:91], v[90:91], v[90:91], v[92:93]
	v_mov_b32_e32 v88, v43
	v_mov_b32_e32 v89, v47
	v_pk_fma_f32 v[58:59], v[58:59], v[58:59], v[90:91]
	s_nop 0
	v_pk_fma_f32 v[58:59], v[88:89], v[88:89], v[58:59]
	s_nop 0
	v_mov_b32_e32 v60, v58
	v_pk_add_f32 v[56:57], v[56:57], v[60:61]
	v_mov_b32_e32 v52, v59
	v_pk_add_f32 v[52:53], v[56:57], v[52:53]
	s_nop 1
	v_mov_b32_dpp v57, v53 quad_perm:[1,0,3,2] row_mask:0xf bank_mask:0xf bound_ctrl:1
	v_mov_b32_dpp v56, v52 quad_perm:[1,0,3,2] row_mask:0xf bank_mask:0xf bound_ctrl:1
	v_pk_add_f32 v[52:53], v[52:53], v[56:57]
	s_nop 1
	v_mov_b32_dpp v57, v53 quad_perm:[2,3,0,1] row_mask:0xf bank_mask:0xf bound_ctrl:1
	v_mov_b32_dpp v56, v52 quad_perm:[2,3,0,1] row_mask:0xf bank_mask:0xf bound_ctrl:1
	v_pk_add_f32 v[52:53], v[52:53], v[56:57]
	s_nop 1
	v_mov_b32_dpp v57, v53 row_half_mirror row_mask:0xf bank_mask:0xf bound_ctrl:1
	v_mov_b32_dpp v56, v52 row_half_mirror row_mask:0xf bank_mask:0xf bound_ctrl:1
	v_pk_add_f32 v[52:53], v[52:53], v[56:57]
	s_nop 1
	v_mov_b32_dpp v57, v53 row_ror:8 row_mask:0xf bank_mask:0xf bound_ctrl:1
	v_mov_b32_dpp v56, v52 row_ror:8 row_mask:0xf bank_mask:0xf bound_ctrl:1
	v_pk_add_f32 v[52:53], v[52:53], v[56:57]
	ds_bpermute_b32 v57, v64, v53
	ds_bpermute_b32 v56, v64, v52
	s_waitcnt lgkmcnt(0)
	v_pk_add_f32 v[52:53], v[52:53], v[56:57]
	ds_bpermute_b32 v57, v65, v53
	ds_bpermute_b32 v56, v65, v52
	s_waitcnt lgkmcnt(0)
	v_pk_add_f32 v[52:53], v[52:53], v[56:57]
	s_nop 0
	v_pk_fma_f32 v[52:53], v[52:53], s[12:13], v[66:67] op_sel_hi:[1,0,0]
	s_nop 0
	v_mul_f32_e32 v51, 0x4b800000, v53
	v_cmp_gt_f32_e64 s[0:1], s8, v53
	v_cmp_gt_f32_e32 vcc, s8, v52
	s_nop 0
	v_cndmask_b32_e64 v51, v53, v51, s[0:1]
	v_rsq_f32_e32 v51, v51
	s_nop 0
	v_mul_f32_e32 v53, 0x45800000, v51
	v_cndmask_b32_e64 v56, v51, v53, s[0:1]
	v_pk_mul_f32 v[16:17], v[16:17], v[56:57] op_sel_hi:[1,0]
	v_pk_mul_f32 v[18:19], v[18:19], v[56:57] op_sel_hi:[1,0]
	v_pk_mul_f32 v[16:17], v[0:1], v[16:17]
	v_pk_mul_f32 v[18:19], v[2:3], v[18:19]
	v_cvt_pk_bf16_f32 v16, v16, v17
	v_cvt_pk_bf16_f32 v17, v18, v19
	v_pk_mul_f32 v[18:19], v[20:21], v[56:57] op_sel_hi:[1,0]
	v_pk_mul_f32 v[20:21], v[22:23], v[56:57] op_sel_hi:[1,0]
	v_pk_mul_f32 v[18:19], v[4:5], v[18:19]
	v_pk_mul_f32 v[20:21], v[6:7], v[20:21]
	v_cvt_pk_bf16_f32 v18, v18, v19
	v_cvt_pk_bf16_f32 v19, v20, v21
	v_pk_mul_f32 v[20:21], v[24:25], v[56:57] op_sel_hi:[1,0]
	v_pk_mul_f32 v[22:23], v[26:27], v[56:57] op_sel_hi:[1,0]
	v_pk_mul_f32 v[20:21], v[8:9], v[20:21]
	v_pk_mul_f32 v[22:23], v[10:11], v[22:23]
	v_cvt_pk_bf16_f32 v20, v20, v21
	v_cvt_pk_bf16_f32 v21, v22, v23
	v_pk_mul_f32 v[22:23], v[28:29], v[56:57] op_sel_hi:[1,0]
	v_pk_mul_f32 v[24:25], v[30:31], v[56:57] op_sel_hi:[1,0]
	v_pk_mul_f32 v[22:23], v[12:13], v[22:23]
	v_pk_mul_f32 v[24:25], v[14:15], v[24:25]
	v_cvt_pk_bf16_f32 v22, v22, v23
	v_cvt_pk_bf16_f32 v23, v24, v25
	global_store_dwordx2 v[54:55], v[16:17], off
	global_store_dwordx2 v[54:55], v[18:19], off offset:512
	global_store_dwordx2 v[54:55], v[20:21], off offset:1024
	global_store_dwordx2 v[54:55], v[22:23], off offset:1536
	v_mul_f32_e32 v16, 0x4b800000, v52
	v_cndmask_b32_e32 v16, v52, v16, vcc
	v_rsq_f32_e32 v16, v16
	s_mov_b32 s0, 0x17fff
	v_mul_f32_e32 v17, 0x45800000, v16
	v_cndmask_b32_e32 v16, v16, v17, vcc
	v_pk_mul_f32 v[18:19], v[32:33], v[16:17] op_sel_hi:[1,0]
	v_pk_mul_f32 v[20:21], v[34:35], v[16:17] op_sel_hi:[1,0]
	v_pk_mul_f32 v[18:19], v[0:1], v[18:19]
	v_pk_mul_f32 v[20:21], v[2:3], v[20:21]
	v_cvt_pk_bf16_f32 v18, v18, v19
	v_cvt_pk_bf16_f32 v19, v20, v21
	global_store_dwordx2 v[84:85], v[18:19], off
	v_pk_mul_f32 v[18:19], v[36:37], v[16:17] op_sel_hi:[1,0]
	v_pk_mul_f32 v[20:21], v[38:39], v[16:17] op_sel_hi:[1,0]
	v_pk_mul_f32 v[18:19], v[4:5], v[18:19]
	v_pk_mul_f32 v[20:21], v[6:7], v[20:21]
	v_cvt_pk_bf16_f32 v18, v18, v19
	v_cvt_pk_bf16_f32 v19, v20, v21
	global_store_dwordx2 v[84:85], v[18:19], off offset:512
	v_pk_mul_f32 v[18:19], v[40:41], v[16:17] op_sel_hi:[1,0]
	v_pk_mul_f32 v[20:21], v[42:43], v[16:17] op_sel_hi:[1,0]
	v_pk_mul_f32 v[18:19], v[8:9], v[18:19]
	v_pk_mul_f32 v[20:21], v[10:11], v[20:21]
	v_cvt_pk_bf16_f32 v18, v18, v19
	v_cvt_pk_bf16_f32 v19, v20, v21
	global_store_dwordx2 v[84:85], v[18:19], off offset:1024
	v_pk_mul_f32 v[18:19], v[44:45], v[16:17] op_sel_hi:[1,0]
	v_pk_mul_f32 v[16:17], v[46:47], v[16:17] op_sel_hi:[1,0]
	v_pk_mul_f32 v[18:19], v[12:13], v[18:19]
	v_pk_mul_f32 v[16:17], v[14:15], v[16:17]
	v_cvt_pk_bf16_f32 v18, v18, v19
	v_cvt_pk_bf16_f32 v19, v16, v17
	v_add_u32_e32 v16, -3, v50
	v_cmp_gt_i32_e32 vcc, 0, v16
	s_or_b64 s[6:7], vcc, s[6:7]
	global_store_dwordx2 v[84:85], v[18:19], off offset:1536
	s_andn2_b64 exec, exec, s[6:7]
	s_cbranch_execnz .LBB0_2920
